# E50a: layer-1 memory-attention unit (loop body + peeled last tile): K-fragment and transposed-V LDS reads issued through a 6-deep rolling register window ahead of the MFMAs, counted lgkmcnt; on E41
# speedup vs baseline: 1.0019x; 1.0019x over previous
.LBB0_1242:
	v_pk_add_f32 v[16:17], v[82:83], v[158:159] op_sel_hi:[1,0] neg_lo:[0,1] neg_hi:[0,1]
	v_pk_add_f32 v[84:85], v[84:85], v[158:159] op_sel_hi:[1,0] neg_lo:[0,1] neg_hi:[0,1]
	v_exp_f32_e32 v82, v16
	v_exp_f32_e32 v83, v17
	v_exp_f32_e32 v84, v84
	v_exp_f32_e32 v85, v85
	v_pk_add_f32 v[86:87], v[86:87], v[158:159] op_sel_hi:[1,0] neg_lo:[0,1] neg_hi:[0,1]
	v_pk_add_f32 v[16:17], v[82:83], 0 op_sel_hi:[1,0]
	v_exp_f32_e32 v198, v86
	v_exp_f32_e32 v199, v87
	v_pk_add_f32 v[86:87], v[88:89], v[158:159] op_sel_hi:[1,0] neg_lo:[0,1] neg_hi:[0,1]
	v_pk_add_f32 v[16:17], v[84:85], v[16:17]
	v_exp_f32_e32 v200, v86
	v_exp_f32_e32 v201, v87
	v_pk_add_f32 v[86:87], v[90:91], v[158:159] op_sel_hi:[1,0] neg_lo:[0,1] neg_hi:[0,1]
	v_pk_add_f32 v[16:17], v[198:199], v[16:17]
	v_exp_f32_e32 v168, v86
	v_exp_f32_e32 v169, v87
	v_pk_add_f32 v[86:87], v[92:93], v[158:159] op_sel_hi:[1,0] neg_lo:[0,1] neg_hi:[0,1]
	v_pk_add_f32 v[16:17], v[200:201], v[16:17]
	v_exp_f32_e32 v170, v86
	v_exp_f32_e32 v171, v87
	v_pk_add_f32 v[86:87], v[94:95], v[158:159] op_sel_hi:[1,0] neg_lo:[0,1] neg_hi:[0,1]
	v_pk_add_f32 v[16:17], v[168:169], v[16:17]
	v_exp_f32_e32 v172, v86
	v_exp_f32_e32 v173, v87
	v_pk_add_f32 v[86:87], v[96:97], v[158:159] op_sel_hi:[1,0] neg_lo:[0,1] neg_hi:[0,1]
	v_pk_add_f32 v[16:17], v[170:171], v[16:17]
	v_exp_f32_e32 v174, v86
	v_exp_f32_e32 v175, v87
	v_pk_add_f32 v[86:87], v[98:99], v[158:159] op_sel_hi:[1,0] neg_lo:[0,1] neg_hi:[0,1]
	v_pk_add_f32 v[16:17], v[172:173], v[16:17]
	v_exp_f32_e32 v92, v86
	v_exp_f32_e32 v93, v87
	v_pk_add_f32 v[86:87], v[100:101], v[158:159] op_sel_hi:[1,0] neg_lo:[0,1] neg_hi:[0,1]
	v_pk_add_f32 v[16:17], v[174:175], v[16:17]
	v_exp_f32_e32 v94, v86
	v_exp_f32_e32 v95, v87
	v_pk_add_f32 v[86:87], v[102:103], v[158:159] op_sel_hi:[1,0] neg_lo:[0,1] neg_hi:[0,1]
	v_pk_add_f32 v[16:17], v[92:93], v[16:17]
	v_exp_f32_e32 v96, v86
	v_exp_f32_e32 v97, v87
	v_pk_add_f32 v[86:87], v[104:105], v[158:159] op_sel_hi:[1,0] neg_lo:[0,1] neg_hi:[0,1]
	v_pk_add_f32 v[16:17], v[94:95], v[16:17]
	v_exp_f32_e32 v98, v86
	v_exp_f32_e32 v99, v87
	v_pk_add_f32 v[16:17], v[96:97], v[16:17]
	v_add3_u32 v104, s9, v157, v191
	ds_read_b64_tr_b16 v[226:227], v104 offset:17408
	ds_read_b64_tr_b16 v[228:229], v104 offset:19968
	ds_read_b64_tr_b16 v[230:231], v104 offset:17472
	ds_read_b64_tr_b16 v[232:233], v104 offset:20032
	ds_read_b64_tr_b16 v[234:235], v104 offset:17536
	ds_read_b64_tr_b16 v[236:237], v104 offset:20096
	ds_read_b64_tr_b16 v[238:239], v104 offset:17600
	ds_read_b64_tr_b16 v[240:241], v104 offset:20160
	ds_read_b64_tr_b16 v[246:247], v104 offset:22528
	ds_read_b64_tr_b16 v[248:249], v104 offset:25088
	ds_read_b64_tr_b16 v[250:251], v104 offset:22592
	ds_read_b64_tr_b16 v[252:253], v104 offset:25152
	v_cvt_pk_bf16_f32 v82, v82, v83
	v_pk_add_f32 v[86:87], v[98:99], v[16:17]
	v_pk_add_f32 v[16:17], v[106:107], v[158:159] op_sel_hi:[1,0] neg_lo:[0,1] neg_hi:[0,1]
	v_cvt_pk_bf16_f32 v83, v84, v85
	v_exp_f32_e32 v16, v16
	v_exp_f32_e32 v17, v17
	v_cvt_pk_bf16_f32 v84, v198, v199
	v_cvt_pk_bf16_f32 v85, v200, v201
	v_pk_add_f32 v[88:89], v[16:17], v[86:87]
	v_pk_add_f32 v[86:87], v[108:109], v[158:159] op_sel_hi:[1,0] neg_lo:[0,1] neg_hi:[0,1]
	s_nop 0
	v_exp_f32_e32 v86, v86
	v_exp_f32_e32 v87, v87
	s_nop 0
	v_pk_add_f32 v[90:91], v[86:87], v[88:89]
	v_pk_add_f32 v[88:89], v[110:111], v[158:159] op_sel_hi:[1,0] neg_lo:[0,1] neg_hi:[0,1]
	s_nop 0
	v_exp_f32_e32 v88, v88
	v_exp_f32_e32 v89, v89
	s_nop 0
	v_pk_add_f32 v[100:101], v[88:89], v[90:91]
	v_pk_add_f32 v[90:91], v[112:113], v[158:159] op_sel_hi:[1,0] neg_lo:[0,1] neg_hi:[0,1]
	s_nop 0
	v_exp_f32_e32 v90, v90
	v_exp_f32_e32 v91, v91
	s_nop 0
	v_pk_add_f32 v[100:101], v[90:91], v[100:101]
	s_nop 0
	v_add_f32_e32 v2, v100, v101
	s_waitcnt lgkmcnt(10)
	v_mfma_f32_32x32x16_bf16 v[66:81], v[226:229], v[82:85], v[66:81]
	ds_read_b64_tr_b16 v[226:227], v104 offset:22656
	ds_read_b64_tr_b16 v[228:229], v104 offset:25216
	v_add_f32_e32 v153, v153, v2
	s_waitcnt lgkmcnt(10)
	v_mfma_f32_32x32x16_bf16 v[50:65], v[230:233], v[82:85], v[50:65]
	ds_read_b64_tr_b16 v[230:231], v104 offset:22720
	ds_read_b64_tr_b16 v[232:233], v104 offset:25280
	s_waitcnt lgkmcnt(10)
	v_mfma_f32_32x32x16_bf16 v[34:49], v[234:237], v[82:85], v[34:49]
	ds_read_b64_tr_b16 v[234:235], v104 offset:27648
	ds_read_b64_tr_b16 v[236:237], v104 offset:30208
	s_waitcnt lgkmcnt(10)
	v_mfma_f32_32x32x16_bf16 v[18:33], v[238:241], v[82:85], v[18:33]
	ds_read_b64_tr_b16 v[238:239], v104 offset:27712
	ds_read_b64_tr_b16 v[240:241], v104 offset:30272
	v_cvt_pk_bf16_f32 v82, v168, v169
	v_cvt_pk_bf16_f32 v83, v170, v171
	v_cvt_pk_bf16_f32 v84, v172, v173
	v_cvt_pk_bf16_f32 v85, v174, v175
	s_nop 0
	s_waitcnt lgkmcnt(10)
	v_mfma_f32_32x32x16_bf16 v[66:81], v[246:249], v[82:85], v[66:81]
	ds_read_b64_tr_b16 v[246:247], v104 offset:27776
	ds_read_b64_tr_b16 v[248:249], v104 offset:30336
	s_waitcnt lgkmcnt(10)
	v_mfma_f32_32x32x16_bf16 v[50:65], v[250:253], v[82:85], v[50:65]
	ds_read_b64_tr_b16 v[250:251], v104 offset:27840
	ds_read_b64_tr_b16 v[252:253], v104 offset:30400
	s_waitcnt lgkmcnt(10)
	v_mfma_f32_32x32x16_bf16 v[34:49], v[226:229], v[82:85], v[34:49]
	ds_read_b64_tr_b16 v[226:227], v104 offset:32768
	ds_read_b64_tr_b16 v[228:229], v104 offset:35328
	s_waitcnt lgkmcnt(10)
	v_mfma_f32_32x32x16_bf16 v[18:33], v[230:233], v[82:85], v[18:33]
	ds_read_b64_tr_b16 v[230:231], v104 offset:32832
	ds_read_b64_tr_b16 v[232:233], v104 offset:35392
	v_cvt_pk_bf16_f32 v82, v92, v93
	v_cvt_pk_bf16_f32 v83, v94, v95
	v_cvt_pk_bf16_f32 v84, v96, v97
	v_cvt_pk_bf16_f32 v85, v98, v99
	s_nop 0
	s_waitcnt lgkmcnt(10)
	v_mfma_f32_32x32x16_bf16 v[66:81], v[234:237], v[82:85], v[66:81]
	ds_read_b64_tr_b16 v[234:235], v104 offset:32896
	ds_read_b64_tr_b16 v[236:237], v104 offset:35456
	s_waitcnt lgkmcnt(10)
	v_mfma_f32_32x32x16_bf16 v[50:65], v[238:241], v[82:85], v[50:65]
	ds_read_b64_tr_b16 v[238:239], v104 offset:32960
	ds_read_b64_tr_b16 v[240:241], v104 offset:35520
	s_waitcnt lgkmcnt(10)
	v_mfma_f32_32x32x16_bf16 v[34:49], v[246:249], v[82:85], v[34:49]
	s_waitcnt lgkmcnt(8)
	v_mfma_f32_32x32x16_bf16 v[18:33], v[250:253], v[82:85], v[18:33]
	v_cvt_pk_bf16_f32 v83, v86, v87
	v_cvt_pk_bf16_f32 v84, v88, v89
	v_cvt_pk_bf16_f32 v82, v16, v17
	v_cvt_pk_bf16_f32 v85, v90, v91
	s_nop 0
	s_waitcnt lgkmcnt(6)
	v_mfma_f32_32x32x16_bf16 v[66:81], v[226:229], v[82:85], v[66:81]
	s_waitcnt lgkmcnt(4)
	v_mfma_f32_32x32x16_bf16 v[50:65], v[230:233], v[82:85], v[50:65]
	s_waitcnt lgkmcnt(2)
	v_mfma_f32_32x32x16_bf16 v[34:49], v[234:237], v[82:85], v[34:49]
	s_waitcnt lgkmcnt(0)
	v_mfma_f32_32x32x16_bf16 v[18:33], v[238:241], v[82:85], v[18:33]

.LBB0_1244:
	v_lshl_add_u64 v[4:5], v[164:165], 0, s[36:37]
	v_lshl_add_u64 v[8:9], v[166:167], 0, s[36:37]
	v_lshl_add_u64 v[12:13], v[160:161], 0, s[36:37]
	v_lshl_add_u64 v[16:17], v[162:163], 0, s[36:37]
	global_load_dwordx4 v[4:7], v[4:5], off
	v_cndmask_b32_e64 v2, 0, 1, s[20:21]
	global_load_dwordx4 v[8:11], v[8:9], off
	v_cmp_ne_u32_e64 s[18:19], 1, v2
	global_load_dwordx4 v[12:15], v[12:13], off
	s_andn2_b64 vcc, exec, s[20:21]
	global_load_dwordx4 v[146:149], v[16:17], off
	s_cbranch_vccnz .LBB0_1243
	s_bitcmp1_b32 s8, 0
	s_cselect_b32 s9, 0x9400, 0
	s_add_i32 s9, s9, 0
	v_add3_u32 v2, s9, v214, v159
	ds_read_b128 v[226:229], v2
	ds_read_b128 v[230:233], v2 offset:32
	ds_read_b128 v[234:237], v2 offset:64
	ds_read_b128 v[238:241], v2 offset:96
	ds_read_b128 v[246:249], v2 offset:128
	ds_read_b128 v[250:253], v2 offset:160
	s_waitcnt lgkmcnt(5)
	v_mfma_f32_32x32x16_bf16 v[82:97], v[226:229], v[142:145], 0
	ds_read_b128 v[226:229], v2 offset:192
	s_waitcnt lgkmcnt(5)
	v_mfma_f32_32x32x16_bf16 v[82:97], v[230:233], v[138:141], v[82:97]
	ds_read_b128 v[230:233], v2 offset:224
	s_waitcnt lgkmcnt(5)
	v_mfma_f32_32x32x16_bf16 v[82:97], v[234:237], v[134:137], v[82:97]
	ds_read_b128 v[234:237], v2 offset:8704
	s_waitcnt lgkmcnt(5)
	v_mfma_f32_32x32x16_bf16 v[82:97], v[238:241], v[130:133], v[82:97]
	ds_read_b128 v[238:241], v2 offset:8736
	s_waitcnt lgkmcnt(5)
	v_mfma_f32_32x32x16_bf16 v[82:97], v[246:249], v[126:129], v[82:97]
	ds_read_b128 v[246:249], v2 offset:8768
	s_waitcnt lgkmcnt(5)
	v_mfma_f32_32x32x16_bf16 v[82:97], v[250:253], v[122:125], v[82:97]
	ds_read_b128 v[250:253], v2 offset:8800
	s_waitcnt lgkmcnt(5)
	v_mfma_f32_32x32x16_bf16 v[82:97], v[226:229], v[118:121], v[82:97]
	ds_read_b128 v[226:229], v2 offset:8832
	s_waitcnt lgkmcnt(5)
	v_mfma_f32_32x32x16_bf16 v[82:97], v[230:233], v[114:117], v[82:97]
	ds_read_b128 v[230:233], v2 offset:8864
	s_waitcnt lgkmcnt(5)
	v_mfma_f32_32x32x16_bf16 v[98:113], v[234:237], v[142:145], 0
	ds_read_b128 v[234:237], v2 offset:8896
	s_waitcnt lgkmcnt(5)
	v_mfma_f32_32x32x16_bf16 v[98:113], v[238:241], v[138:141], v[98:113]
	ds_read_b128 v[238:241], v2 offset:8928
	s_waitcnt lgkmcnt(5)
	v_mfma_f32_32x32x16_bf16 v[98:113], v[246:249], v[134:137], v[98:113]
	s_waitcnt lgkmcnt(4)
	v_mfma_f32_32x32x16_bf16 v[98:113], v[250:253], v[130:133], v[98:113]
	s_waitcnt lgkmcnt(3)
	v_mfma_f32_32x32x16_bf16 v[98:113], v[226:229], v[126:129], v[98:113]
	s_waitcnt lgkmcnt(2)
	v_mfma_f32_32x32x16_bf16 v[98:113], v[230:233], v[122:125], v[98:113]
	s_waitcnt lgkmcnt(1)
	v_mfma_f32_32x32x16_bf16 v[98:113], v[234:237], v[118:121], v[98:113]
	v_max3_f32 v2, v82, v83, v84
	v_max3_f32 v2, v2, v85, v86
	v_max3_f32 v2, v2, v87, v88
	v_max3_f32 v2, v2, v89, v90
	v_max3_f32 v2, v2, v91, v92
	v_max3_f32 v2, v2, v93, v94
	s_waitcnt lgkmcnt(0)
	v_mfma_f32_32x32x16_bf16 v[98:113], v[238:241], v[114:117], v[98:113]
	v_max3_f32 v2, v2, v95, v96
	s_nop 10
	v_max_f32_e32 v16, v99, v99
	v_max_f32_e32 v17, v98, v98
	v_max_f32_e32 v16, v17, v16
	v_max3_f32 v16, v16, v100, v101
	v_max3_f32 v16, v16, v102, v103
	v_max3_f32 v16, v16, v104, v105
	v_max3_f32 v16, v16, v106, v107
	v_max3_f32 v16, v16, v108, v109
	v_max3_f32 v16, v16, v110, v111
	v_max3_f32 v16, v16, v112, v113
	v_max3_f32 v2, v2, v97, v16
	v_mov_b32_e32 v16, v2
	s_nop 1
	v_permlane32_swap_b32_e32 v2, v16
	v_max_f32_e32 v16, v16, v16
	v_max_f32_e32 v2, v2, v2
	v_max_f32_e32 v2, v2, v16
	v_add_f32_e32 v16, 0x41a00000, v158
	v_cmp_gt_f32_e32 vcc, v2, v16
	s_cbranch_vccz .LBB0_1242
	v_max_f32_e32 v2, v2, v2
	v_max_f32_e32 v16, v158, v158
	v_max_f32_e32 v16, v16, v2
	v_sub_f32_e32 v2, v158, v16
	v_exp_f32_e32 v2, v2
	v_mov_b32_e32 v158, v16
	v_pk_mul_f32 v[80:81], v[80:81], v[2:3] op_sel_hi:[1,0]
	v_pk_mul_f32 v[78:79], v[78:79], v[2:3] op_sel_hi:[1,0]
	v_pk_mul_f32 v[76:77], v[76:77], v[2:3] op_sel_hi:[1,0]
	v_pk_mul_f32 v[74:75], v[74:75], v[2:3] op_sel_hi:[1,0]
	v_pk_mul_f32 v[72:73], v[72:73], v[2:3] op_sel_hi:[1,0]
	v_pk_mul_f32 v[70:71], v[70:71], v[2:3] op_sel_hi:[1,0]
	v_pk_mul_f32 v[68:69], v[68:69], v[2:3] op_sel_hi:[1,0]
	v_pk_mul_f32 v[66:67], v[66:67], v[2:3] op_sel_hi:[1,0]
	v_pk_mul_f32 v[64:65], v[64:65], v[2:3] op_sel_hi:[1,0]
	v_pk_mul_f32 v[62:63], v[62:63], v[2:3] op_sel_hi:[1,0]
	v_pk_mul_f32 v[60:61], v[60:61], v[2:3] op_sel_hi:[1,0]
	v_pk_mul_f32 v[58:59], v[58:59], v[2:3] op_sel_hi:[1,0]
	v_pk_mul_f32 v[56:57], v[56:57], v[2:3] op_sel_hi:[1,0]
	v_pk_mul_f32 v[54:55], v[54:55], v[2:3] op_sel_hi:[1,0]
	v_pk_mul_f32 v[52:53], v[52:53], v[2:3] op_sel_hi:[1,0]
	v_pk_mul_f32 v[50:51], v[50:51], v[2:3] op_sel_hi:[1,0]
	v_pk_mul_f32 v[48:49], v[48:49], v[2:3] op_sel_hi:[1,0]
	v_pk_mul_f32 v[46:47], v[46:47], v[2:3] op_sel_hi:[1,0]
	v_pk_mul_f32 v[44:45], v[44:45], v[2:3] op_sel_hi:[1,0]
	v_pk_mul_f32 v[42:43], v[42:43], v[2:3] op_sel_hi:[1,0]
	v_pk_mul_f32 v[40:41], v[40:41], v[2:3] op_sel_hi:[1,0]
	v_pk_mul_f32 v[38:39], v[38:39], v[2:3] op_sel_hi:[1,0]
	v_pk_mul_f32 v[36:37], v[36:37], v[2:3] op_sel_hi:[1,0]
	v_pk_mul_f32 v[34:35], v[34:35], v[2:3] op_sel_hi:[1,0]
	v_pk_mul_f32 v[32:33], v[32:33], v[2:3] op_sel_hi:[1,0]
	v_pk_mul_f32 v[30:31], v[30:31], v[2:3] op_sel_hi:[1,0]
	v_pk_mul_f32 v[28:29], v[28:29], v[2:3] op_sel_hi:[1,0]
	v_pk_mul_f32 v[26:27], v[26:27], v[2:3] op_sel_hi:[1,0]
	v_pk_mul_f32 v[24:25], v[24:25], v[2:3] op_sel_hi:[1,0]
	v_pk_mul_f32 v[22:23], v[22:23], v[2:3] op_sel_hi:[1,0]
	v_pk_mul_f32 v[20:21], v[20:21], v[2:3] op_sel_hi:[1,0]
	v_pk_mul_f32 v[18:19], v[18:19], v[2:3] op_sel_hi:[1,0]
	v_mul_f32_e32 v153, v153, v2
	s_branch .LBB0_1242
.LBB0_1247:
	s_and_b64 vcc, exec, s[18:19]
	s_cbranch_vccnz .LBB0_1251
	v_add_u32_e32 v2, v176, v159
	ds_read_b128 v[226:229], v2 offset:37888
	ds_read_b128 v[230:233], v2 offset:37920
	ds_read_b128 v[234:237], v2 offset:37952
	ds_read_b128 v[238:241], v2 offset:37984
	ds_read_b128 v[246:249], v2 offset:38016
	ds_read_b128 v[250:253], v2 offset:38048
	s_waitcnt lgkmcnt(5)
	v_mfma_f32_32x32x16_bf16 v[98:113], v[226:229], v[142:145], 0
	ds_read_b128 v[226:229], v2 offset:38080
	s_waitcnt lgkmcnt(5)
	v_mfma_f32_32x32x16_bf16 v[98:113], v[230:233], v[138:141], v[98:113]
	ds_read_b128 v[230:233], v2 offset:38112
	s_waitcnt lgkmcnt(5)
	v_mfma_f32_32x32x16_bf16 v[98:113], v[234:237], v[134:137], v[98:113]
	ds_read_b128 v[234:237], v2 offset:46592
	s_waitcnt lgkmcnt(5)
	v_mfma_f32_32x32x16_bf16 v[98:113], v[238:241], v[130:133], v[98:113]
	ds_read_b128 v[238:241], v2 offset:46624
	s_waitcnt lgkmcnt(5)
	v_mfma_f32_32x32x16_bf16 v[98:113], v[246:249], v[126:129], v[98:113]
	ds_read_b128 v[246:249], v2 offset:46656
	s_waitcnt lgkmcnt(5)
	v_mfma_f32_32x32x16_bf16 v[98:113], v[250:253], v[122:125], v[98:113]
	ds_read_b128 v[250:253], v2 offset:46688
	s_waitcnt lgkmcnt(5)
	v_mfma_f32_32x32x16_bf16 v[98:113], v[226:229], v[118:121], v[98:113]
	ds_read_b128 v[226:229], v2 offset:46720
	s_waitcnt lgkmcnt(5)
	v_mfma_f32_32x32x16_bf16 v[98:113], v[230:233], v[114:117], v[98:113]
	ds_read_b128 v[230:233], v2 offset:46752
	s_waitcnt lgkmcnt(5)
	v_mfma_f32_32x32x16_bf16 v[82:97], v[234:237], v[142:145], 0
	ds_read_b128 v[234:237], v2 offset:46784
	s_waitcnt lgkmcnt(5)
	v_mfma_f32_32x32x16_bf16 v[82:97], v[238:241], v[138:141], v[82:97]
	ds_read_b128 v[238:241], v2 offset:46816
	s_waitcnt lgkmcnt(5)
	v_mfma_f32_32x32x16_bf16 v[82:97], v[246:249], v[134:137], v[82:97]
	s_waitcnt lgkmcnt(4)
	v_mfma_f32_32x32x16_bf16 v[82:97], v[250:253], v[130:133], v[82:97]
	s_waitcnt lgkmcnt(3)
	v_mfma_f32_32x32x16_bf16 v[82:97], v[226:229], v[126:129], v[82:97]
	s_waitcnt lgkmcnt(2)
	v_mfma_f32_32x32x16_bf16 v[82:97], v[230:233], v[122:125], v[82:97]
	v_max3_f32 v2, v98, v99, v100
	v_max3_f32 v2, v2, v101, v102
	v_max3_f32 v2, v2, v103, v104
	v_max3_f32 v2, v2, v105, v106
	v_max3_f32 v2, v2, v107, v108
	v_max3_f32 v2, v2, v109, v110
	s_waitcnt lgkmcnt(1)
	v_mfma_f32_32x32x16_bf16 v[82:97], v[234:237], v[118:121], v[82:97]
	v_max3_f32 v2, v2, v111, v112
	s_waitcnt lgkmcnt(0)
	v_mfma_f32_32x32x16_bf16 v[82:97], v[238:241], v[114:117], v[82:97]
	s_nop 11
	v_max_f32_e32 v4, v83, v83
	v_max_f32_e32 v5, v82, v82
	v_max_f32_e32 v4, v5, v4
	v_max3_f32 v4, v4, v84, v85
	v_max3_f32 v4, v4, v86, v87
	v_max3_f32 v4, v4, v88, v89
	v_max3_f32 v4, v4, v90, v91
	v_max3_f32 v4, v4, v92, v93
	v_max3_f32 v4, v4, v94, v95
	v_max3_f32 v4, v4, v96, v97
	v_max3_f32 v2, v2, v113, v4
	v_mov_b32_e32 v4, v2
	s_nop 1
	v_permlane32_swap_b32_e32 v2, v4
	v_max_f32_e32 v4, v4, v4
	v_max_f32_e32 v2, v2, v2
	v_max_f32_e32 v2, v2, v4
	v_add_f32_e32 v4, 0x41a00000, v158
	v_cmp_gt_f32_e32 vcc, v2, v4
	s_cbranch_vccz .LBB0_1250
	v_max_f32_e32 v2, v2, v2
	v_max_f32_e32 v4, v158, v158
	v_max_f32_e32 v4, v4, v2
	v_sub_f32_e32 v2, v158, v4
	v_exp_f32_e32 v2, v2
	v_mov_b32_e32 v158, v4
	v_pk_mul_f32 v[80:81], v[80:81], v[2:3] op_sel_hi:[1,0]
	v_pk_mul_f32 v[78:79], v[78:79], v[2:3] op_sel_hi:[1,0]
	v_pk_mul_f32 v[76:77], v[76:77], v[2:3] op_sel_hi:[1,0]
	v_pk_mul_f32 v[74:75], v[74:75], v[2:3] op_sel_hi:[1,0]
	v_pk_mul_f32 v[72:73], v[72:73], v[2:3] op_sel_hi:[1,0]
	v_pk_mul_f32 v[70:71], v[70:71], v[2:3] op_sel_hi:[1,0]
	v_pk_mul_f32 v[68:69], v[68:69], v[2:3] op_sel_hi:[1,0]
	v_pk_mul_f32 v[66:67], v[66:67], v[2:3] op_sel_hi:[1,0]
	v_pk_mul_f32 v[64:65], v[64:65], v[2:3] op_sel_hi:[1,0]
	v_pk_mul_f32 v[62:63], v[62:63], v[2:3] op_sel_hi:[1,0]
	v_pk_mul_f32 v[60:61], v[60:61], v[2:3] op_sel_hi:[1,0]
	v_pk_mul_f32 v[58:59], v[58:59], v[2:3] op_sel_hi:[1,0]
	v_pk_mul_f32 v[56:57], v[56:57], v[2:3] op_sel_hi:[1,0]
	v_pk_mul_f32 v[54:55], v[54:55], v[2:3] op_sel_hi:[1,0]
	v_pk_mul_f32 v[52:53], v[52:53], v[2:3] op_sel_hi:[1,0]
	v_pk_mul_f32 v[50:51], v[50:51], v[2:3] op_sel_hi:[1,0]
	v_pk_mul_f32 v[48:49], v[48:49], v[2:3] op_sel_hi:[1,0]
	v_pk_mul_f32 v[46:47], v[46:47], v[2:3] op_sel_hi:[1,0]
	v_pk_mul_f32 v[44:45], v[44:45], v[2:3] op_sel_hi:[1,0]
	v_pk_mul_f32 v[42:43], v[42:43], v[2:3] op_sel_hi:[1,0]
	v_pk_mul_f32 v[40:41], v[40:41], v[2:3] op_sel_hi:[1,0]
	v_pk_mul_f32 v[38:39], v[38:39], v[2:3] op_sel_hi:[1,0]
	v_pk_mul_f32 v[36:37], v[36:37], v[2:3] op_sel_hi:[1,0]
	v_pk_mul_f32 v[34:35], v[34:35], v[2:3] op_sel_hi:[1,0]
	v_pk_mul_f32 v[32:33], v[32:33], v[2:3] op_sel_hi:[1,0]
	v_pk_mul_f32 v[30:31], v[30:31], v[2:3] op_sel_hi:[1,0]
	v_pk_mul_f32 v[28:29], v[28:29], v[2:3] op_sel_hi:[1,0]
	v_pk_mul_f32 v[26:27], v[26:27], v[2:3] op_sel_hi:[1,0]
	v_pk_mul_f32 v[24:25], v[24:25], v[2:3] op_sel_hi:[1,0]
	v_pk_mul_f32 v[22:23], v[22:23], v[2:3] op_sel_hi:[1,0]
	v_pk_mul_f32 v[20:21], v[20:21], v[2:3] op_sel_hi:[1,0]
	v_pk_mul_f32 v[18:19], v[18:19], v[2:3] op_sel_hi:[1,0]
	v_mul_f32_e32 v153, v153, v2
.LBB0_1250:
	v_pk_add_f32 v[4:5], v[98:99], v[158:159] op_sel_hi:[1,0] neg_lo:[0,1] neg_hi:[0,1]
	v_add3_u32 v2, 0, v157, v191
	v_add_u32_e32 v243, 0xd800, v2
	ds_read_b64_tr_b16 v[226:227], v2 offset:55296
	ds_read_b64_tr_b16 v[228:229], v2 offset:57856
	ds_read_b64_tr_b16 v[230:231], v2 offset:55360
	ds_read_b64_tr_b16 v[232:233], v2 offset:57920
	ds_read_b64_tr_b16 v[234:235], v2 offset:55424
	ds_read_b64_tr_b16 v[236:237], v2 offset:57984
	ds_read_b64_tr_b16 v[238:239], v2 offset:55488
	ds_read_b64_tr_b16 v[240:241], v2 offset:58048
	ds_read_b64_tr_b16 v[246:247], v2 offset:60416
	ds_read_b64_tr_b16 v[248:249], v2 offset:62976
	ds_read_b64_tr_b16 v[250:251], v2 offset:60480
	ds_read_b64_tr_b16 v[252:253], v2 offset:63040
	v_exp_f32_e32 v8, v4
	v_exp_f32_e32 v9, v5
	v_pk_add_f32 v[4:5], v[100:101], v[158:159] op_sel_hi:[1,0] neg_lo:[0,1] neg_hi:[0,1]
	v_exp_f32_e32 v10, v4
	v_exp_f32_e32 v11, v5
	v_pk_add_f32 v[4:5], v[102:103], v[158:159] op_sel_hi:[1,0] neg_lo:[0,1] neg_hi:[0,1]
	v_pk_add_f32 v[16:17], v[106:107], v[158:159] op_sel_hi:[1,0] neg_lo:[0,1] neg_hi:[0,1]
	v_exp_f32_e32 v12, v4
	v_exp_f32_e32 v13, v5
	v_pk_add_f32 v[4:5], v[104:105], v[158:159] op_sel_hi:[1,0] neg_lo:[0,1] neg_hi:[0,1]
	v_exp_f32_e32 v14, v4
	v_exp_f32_e32 v15, v5
	v_cvt_pk_bf16_f32 v4, v8, v9
	v_cvt_pk_bf16_f32 v5, v10, v11
	v_cvt_pk_bf16_f32 v6, v12, v13
	v_cvt_pk_bf16_f32 v7, v14, v15
	v_exp_f32_e32 v16, v16
	v_exp_f32_e32 v17, v17
	s_waitcnt lgkmcnt(10)
	v_mfma_f32_32x32x16_bf16 v[66:81], v[226:229], v[4:7], v[66:81]
	ds_read_b64_tr_b16 v[226:227], v2 offset:60544
	ds_read_b64_tr_b16 v[228:229], v2 offset:63104
	v_add_f32_e64 v98, v108, -v158
	v_add_f32_e64 v99, v109, -v158
	v_add_f32_e64 v100, v110, -v158
	v_add_f32_e64 v101, v111, -v158
	v_exp_f32_e32 v98, v98
	v_exp_f32_e32 v99, v99
	v_exp_f32_e32 v100, v100
	v_exp_f32_e32 v101, v101
	v_pk_add_f32 v[8:9], v[8:9], 0 op_sel_hi:[1,0]
	s_waitcnt lgkmcnt(10)
	v_mfma_f32_32x32x16_bf16 v[50:65], v[230:233], v[4:7], v[50:65]
	ds_read_b64_tr_b16 v[230:231], v2 offset:60608
	ds_read_b64_tr_b16 v[232:233], v2 offset:63168
	v_add_f32_e64 v102, v112, -v158
	v_add_f32_e64 v103, v113, -v158
	v_cvt_pk_bf16_f32 v104, v16, v17
	v_exp_f32_e32 v102, v102
	v_exp_f32_e32 v103, v103
	v_cvt_pk_bf16_f32 v105, v98, v99
	v_cvt_pk_bf16_f32 v106, v100, v101
	v_pk_add_f32 v[90:91], v[90:91], v[158:159] op_sel_hi:[1,0] neg_lo:[0,1] neg_hi:[0,1]
	s_waitcnt lgkmcnt(10)
	v_mfma_f32_32x32x16_bf16 v[34:49], v[234:237], v[4:7], v[34:49]
	ds_read_b64_tr_b16 v[234:235], v243 offset:10240
	ds_read_b64_tr_b16 v[236:237], v243 offset:12800
	v_cvt_pk_bf16_f32 v107, v102, v103
	v_add_f32_e64 v8, v10, v8
	v_add_f32_e64 v9, v11, v9
	v_add_f32_e64 v8, v12, v8
	v_add_f32_e64 v9, v13, v9
	v_pk_add_f32 v[8:9], v[14:15], v[8:9]
	s_waitcnt lgkmcnt(10)
	v_mfma_f32_32x32x16_bf16 v[18:33], v[238:241], v[4:7], v[18:33]
	ds_read_b64_tr_b16 v[238:239], v243 offset:10304
	ds_read_b64_tr_b16 v[240:241], v243 offset:12864
	v_exp_f32_e32 v120, v90
	v_exp_f32_e32 v121, v91
	v_pk_add_f32 v[90:91], v[92:93], v[158:159] op_sel_hi:[1,0] neg_lo:[0,1] neg_hi:[0,1]
	v_pk_add_f32 v[8:9], v[16:17], v[8:9]
	s_waitcnt lgkmcnt(10)
	v_mfma_f32_32x32x16_bf16 v[66:81], v[246:249], v[104:107], v[66:81]
	ds_read_b64_tr_b16 v[246:247], v243 offset:10368
	ds_read_b64_tr_b16 v[248:249], v243 offset:12928
	v_add_f32_e64 v4, v82, -v158
	v_add_f32_e64 v5, v83, -v158
	v_add_f32_e64 v6, v84, -v158
	v_add_f32_e64 v7, v85, -v158
	v_add_f32_e64 v82, v86, -v158
	v_add_f32_e64 v83, v87, -v158
	v_pk_add_f32 v[84:85], v[88:89], v[158:159] op_sel_hi:[1,0] neg_lo:[0,1] neg_hi:[0,1]
	v_exp_f32_e32 v4, v4
	v_exp_f32_e32 v5, v5
	v_exp_f32_e32 v6, v6
	s_waitcnt lgkmcnt(10)
	v_mfma_f32_32x32x16_bf16 v[50:65], v[250:253], v[104:107], v[50:65]
	ds_read_b64_tr_b16 v[250:251], v243 offset:10432
	ds_read_b64_tr_b16 v[252:253], v243 offset:12992
	v_exp_f32_e32 v7, v7
	v_exp_f32_e32 v82, v82
	v_exp_f32_e32 v83, v83
	v_exp_f32_e32 v84, v84
	v_exp_f32_e32 v85, v85
	v_cvt_pk_bf16_f32 v86, v4, v5
	v_cvt_pk_bf16_f32 v87, v6, v7
	s_waitcnt lgkmcnt(10)
	v_mfma_f32_32x32x16_bf16 v[34:49], v[226:229], v[104:107], v[34:49]
	ds_read_b64_tr_b16 v[226:227], v243 offset:15360
	ds_read_b64_tr_b16 v[228:229], v243 offset:17920
	v_cvt_pk_bf16_f32 v88, v82, v83
	v_cvt_pk_bf16_f32 v89, v84, v85
	v_exp_f32_e32 v122, v90
	v_exp_f32_e32 v123, v91
	v_pk_add_f32 v[90:91], v[94:95], v[158:159] op_sel_hi:[1,0] neg_lo:[0,1] neg_hi:[0,1]
	v_pk_add_f32 v[8:9], v[98:99], v[8:9]
	s_waitcnt lgkmcnt(10)
	v_mfma_f32_32x32x16_bf16 v[18:33], v[230:233], v[104:107], v[18:33]
	ds_read_b64_tr_b16 v[230:231], v243 offset:15424
	ds_read_b64_tr_b16 v[232:233], v243 offset:17984
	v_pk_add_f32 v[8:9], v[100:101], v[8:9]
	s_nop 0
	v_pk_add_f32 v[8:9], v[102:103], v[8:9]
	s_nop 0
	v_pk_add_f32 v[4:5], v[4:5], v[8:9]
	s_waitcnt lgkmcnt(10)
	v_mfma_f32_32x32x16_bf16 v[66:81], v[234:237], v[86:89], v[66:81]
	ds_read_b64_tr_b16 v[234:235], v243 offset:15488
	ds_read_b64_tr_b16 v[236:237], v243 offset:18048
	v_add_f32_e64 v4, v6, v4
	v_add_f32_e64 v5, v7, v5
	v_add_f32_e64 v4, v82, v4
	v_add_f32_e64 v5, v83, v5
	v_add_f32_e64 v4, v84, v4
	v_add_f32_e64 v5, v85, v5
	v_pk_add_f32 v[4:5], v[120:121], v[4:5]
	s_waitcnt lgkmcnt(10)
	v_mfma_f32_32x32x16_bf16 v[50:65], v[238:241], v[86:89], v[50:65]
	ds_read_b64_tr_b16 v[238:239], v243 offset:15552
	ds_read_b64_tr_b16 v[240:241], v243 offset:18112
	v_add_f32_e64 v4, v122, v4
	v_add_f32_e64 v5, v123, v5
	s_waitcnt lgkmcnt(10)
	v_mfma_f32_32x32x16_bf16 v[34:49], v[246:249], v[86:89], v[34:49]
	v_exp_f32_e32 v112, v90
	v_exp_f32_e32 v113, v91
	v_pk_add_f32 v[90:91], v[96:97], v[158:159] op_sel_hi:[1,0] neg_lo:[0,1] neg_hi:[0,1]
	v_pk_add_f32 v[4:5], v[112:113], v[4:5]
	v_exp_f32_e32 v114, v90
	s_waitcnt lgkmcnt(8)
	v_mfma_f32_32x32x16_bf16 v[18:33], v[250:253], v[86:89], v[18:33]
	v_exp_f32_e32 v115, v91
	v_cvt_pk_bf16_f32 v86, v120, v121
	v_cvt_pk_bf16_f32 v87, v122, v123
	v_cvt_pk_bf16_f32 v88, v112, v113
	v_cvt_pk_bf16_f32 v89, v114, v115
	v_pk_add_f32 v[4:5], v[114:115], v[4:5]
	s_waitcnt lgkmcnt(6)
	v_mfma_f32_32x32x16_bf16 v[66:81], v[226:229], v[86:89], v[66:81]
	v_add_f32_e32 v2, v4, v5
	v_add_f32_e32 v153, v153, v2
	s_waitcnt lgkmcnt(4)
	v_mfma_f32_32x32x16_bf16 v[50:65], v[230:233], v[86:89], v[50:65]
	s_waitcnt lgkmcnt(2)
	v_mfma_f32_32x32x16_bf16 v[34:49], v[234:237], v[86:89], v[34:49]
	s_waitcnt lgkmcnt(0)
	v_mfma_f32_32x32x16_bf16 v[18:33], v[238:241], v[86:89], v[18:33]
